# v35: v32 + rope sin/cos tables computed one (row,k) entry per thread over all 256 workgroups instead of 8-16 entries per thread on 17 workgroups (same f64 series code)
# baseline (speedup 1.0000x reference)
.LBB0_99:
	s_add_u32 s0, s10, 0x80000
	s_addc_u32 s1, s11, 0
	v_writelane_b32 v253, s0, 6
	v_mov_b32_e32 v2, v234
	s_nop 0
	v_writelane_b32 v253, s1, 7
	s_lshl_b32 s0, s2, 9
	v_writelane_b32 v253, s0, 8
	v_add_u32_e32 v16, s0, v2
	s_mov_b64 s[4:5], exec
	s_add_u32 s12, s6, 0xfffffec0
	s_addc_u32 s13, s7, -1
	s_lshl_b32 s52, s46, 9
	s_mov_b32 s30, 0x6dc9c883
	s_mov_b32 s31, 0x3fc45f30
	s_mov_b32 s34, 0x54442d18
	s_mov_b32 s35, 0xc01921fb
	s_mov_b32 s48, 0x33145c07
	s_mov_b32 s49, 0xbcb1a626
	s_mov_b32 s53, 0x10000
	v_mov_b32_e32 v3, 0
.Lrp_loop:
	v_cmp_gt_u32_e32 vcc, 0x10800, v16
	s_and_b64 exec, exec, vcc
	s_cbranch_execz .LBB0_154
	v_cmp_gt_u32_e64 s[0:1], s53, v16
	v_lshrrev_b32_e32 v37, 3, v16
	v_subrev_u32_e32 v38, 0x10000, v16
	v_lshrrev_b32_e32 v39, 4, v38
	v_and_b32_e32 v40, 7, v16
	v_and_b32_e32 v41, 15, v38
	v_lshlrev_b32_e32 v40, 2, v40
	v_add_u32_e32 v40, 0xd0, v40
	v_lshlrev_b32_e32 v41, 2, v41
	v_add_u32_e32 v41, 0xf0, v41
	v_cndmask_b32_e64 v2, v39, v37, s[0:1]
	v_cndmask_b32_e64 v40, v41, v40, s[0:1]
	global_load_dword v36, v40, s[12:13]
	v_lshlrev_b32_e32 v42, 3, v16
	v_cvt_f32_u32_e32 v17, v2
	v_mov_b64_e32 v[4:5], 1.0
	s_mov_b32 s54, 2
	s_mov_b32 s55, 4
	s_waitcnt vmcnt(0)
	v_mul_f32_e32 v6, v36, v17
	v_cvt_f64_f32_e32 v[6:7], v6
	v_mul_f64 v[8:9], v[6:7], s[30:31]
	v_rndne_f64_e32 v[8:9], v[8:9]
	v_fmac_f64_e32 v[6:7], s[34:35], v[8:9]
	v_fmac_f64_e32 v[6:7], s[48:49], v[8:9]
	v_mul_f64 v[8:9], v[6:7], -v[6:7]
	v_mov_b64_e32 v[10:11], 1.0
	v_mov_b64_e32 v[12:13], v[6:7]
.Lrp_series:
	s_add_i32 s0, s54, -1
	s_mul_i32 s0, s0, s54
	v_cvt_f64_i32_e32 v[14:15], s0
	s_add_i32 s56, s0, s55
	v_div_scale_f64 v[18:19], s[0:1], v[14:15], v[14:15], v[8:9]
	v_cvt_f64_u32_e32 v[22:23], s56
	v_rcp_f64_e32 v[24:25], v[18:19]
	v_div_scale_f64 v[26:27], s[0:1], v[22:23], v[22:23], v[8:9]
	v_rcp_f64_e32 v[30:31], v[26:27]
	v_fma_f64 v[32:33], -v[18:19], v[24:25], 1.0
	v_fmac_f64_e32 v[24:25], v[24:25], v[32:33]
	v_fma_f64 v[34:35], -v[18:19], v[24:25], 1.0
	v_fma_f64 v[32:33], -v[26:27], v[30:31], 1.0
	v_fmac_f64_e32 v[30:31], v[30:31], v[32:33]
	v_div_scale_f64 v[20:21], vcc, v[8:9], v[14:15], v[8:9]
	v_fmac_f64_e32 v[24:25], v[24:25], v[34:35]
	v_fma_f64 v[32:33], -v[26:27], v[30:31], 1.0
	v_div_scale_f64 v[28:29], s[0:1], v[8:9], v[22:23], v[8:9]
	v_mul_f64 v[34:35], v[20:21], v[24:25]
	v_fmac_f64_e32 v[30:31], v[30:31], v[32:33]
	v_fma_f64 v[18:19], -v[18:19], v[34:35], v[20:21]
	v_mul_f64 v[20:21], v[28:29], v[30:31]
	v_div_fmas_f64 v[18:19], v[18:19], v[24:25], v[34:35]
	v_fma_f64 v[24:25], -v[26:27], v[20:21], v[28:29]
	s_mov_b64 vcc, s[0:1]
	v_div_fixup_f64 v[14:15], v[18:19], v[14:15], v[8:9]
	v_div_fmas_f64 v[18:19], v[24:25], v[30:31], v[20:21]
	v_mul_f64 v[20:21], v[10:11], v[14:15]
	v_fmac_f64_e32 v[4:5], v[10:11], v[14:15]
	v_div_fixup_f64 v[10:11], v[18:19], v[22:23], v[8:9]
	s_add_i32 s54, s54, 2
	s_add_i32 s55, s55, 4
	v_mul_f64 v[14:15], v[12:13], v[10:11]
	s_cmp_lg_u32 s54, 30
	v_fmac_f64_e32 v[6:7], v[12:13], v[10:11]
	v_mov_b64_e32 v[10:11], v[20:21]
	v_mov_b64_e32 v[12:13], v[14:15]
	s_cbranch_scc1 .Lrp_series
	v_cvt_f32_f64_e32 v7, v[6:7]
	v_cvt_f32_f64_e32 v6, v[4:5]
	global_store_dwordx2 v42, v[6:7], s[10:11]
	v_add_u32_e32 v16, s52, v16
	s_branch .Lrp_loop
